# pebp sum loads hoisted; attention epilogue loads batched; rowmax nop pads trimmed
# speedup vs baseline: 1.0022x; 1.0022x over previous
; #define LAS __attribute__((address_space(3)))
; __device__ __forceinline__ void s2_compress(Frame& F, int l) {
;     if (F.tid < 128) { const float* pp = (const float*)(F.ws + WS_PEBP + l * al1m(SZ_PEBP)); float s = 0.f;
; #pragma unroll
;         for (int p = 0; p < 16; ++p) s += pp[((F.tid >> 6) * 16 + p) * 64 + (F.tid & 63)];
;         ((LAS float*)(F.lds + 131072))[F.tid] = s; }
;     __syncthreads();
.LBB0_569:
	s_and_b64 vcc, exec, s[22:23]
	s_cbranch_vccz .LBB0_418
	v_cmp_gt_i32_e32 vcc, s86, v1
	s_and_saveexec_b64 s[22:23], vcc
	s_cbranch_execz .LBB0_572
	v_lshl_add_u32 v2, v1, 2, 0
	v_add_u32_e32 v6, 0x20000, v2
	v_lshlrev_b32_e32 v2, 4, v1
	s_movk_i32 s4, 0xfc00
	s_add_u32 s16, s54, s83
	v_and_or_b32 v2, v2, s4, v124
	s_addc_u32 s17, s55, 0
	v_ashrrev_i32_e32 v3, 31, v2
	v_lshl_add_u64 v[2:3], v[2:3], 2, s[16:17]
	s_mov_b64 s[16:17], 0x9f00000
	s_mov_b32 s4, 0x9f00000
	v_lshl_add_u64 v[4:5], v[2:3], 0, s[16:17]
	v_add_co_u32_e32 v2, vcc, s4, v2
	s_nop 1
	v_addc_co_u32_e32 v3, vcc, 0, v3, vcc
	global_load_dword v2, v[2:3], off
	global_load_dword v3, v[4:5], off offset:256
	global_load_dword v7, v[4:5], off offset:512
	global_load_dword v8, v[4:5], off offset:768
	global_load_dword v9, v[4:5], off offset:1024
	global_load_dword v10, v[4:5], off offset:1280
	global_load_dword v11, v[4:5], off offset:1536
	global_load_dword v12, v[4:5], off offset:1792
	global_load_dword v13, v[4:5], off offset:2048
	global_load_dword v14, v[4:5], off offset:2304
	global_load_dword v15, v[4:5], off offset:2560
	global_load_dword v16, v[4:5], off offset:2816
	global_load_dword v17, v[4:5], off offset:3072
	global_load_dword v18, v[4:5], off offset:3328
	global_load_dword v19, v[4:5], off offset:3584
	global_load_dword v20, v[4:5], off offset:3840
	s_waitcnt vmcnt(15)
	v_add_f32_e32 v2, 0, v2
	s_waitcnt vmcnt(14)
	v_add_f32_e32 v2, v2, v3
	s_waitcnt vmcnt(13)
	v_add_f32_e32 v2, v2, v7
	s_waitcnt vmcnt(12)
	v_add_f32_e32 v2, v2, v8
	s_waitcnt vmcnt(11)
	v_add_f32_e32 v2, v2, v9
	s_waitcnt vmcnt(10)
	v_add_f32_e32 v2, v2, v10
	s_waitcnt vmcnt(9)
	v_add_f32_e32 v2, v2, v11
	s_waitcnt vmcnt(8)
	v_add_f32_e32 v2, v2, v12
	s_waitcnt vmcnt(7)
	v_add_f32_e32 v2, v2, v13
	s_waitcnt vmcnt(6)
	v_add_f32_e32 v2, v2, v14
	s_waitcnt vmcnt(5)
	v_add_f32_e32 v2, v2, v15
	s_waitcnt vmcnt(4)
	v_add_f32_e32 v2, v2, v16
	s_waitcnt vmcnt(3)
	v_add_f32_e32 v2, v2, v17
	s_waitcnt vmcnt(2)
	v_add_f32_e32 v2, v2, v18
	s_waitcnt vmcnt(1)
	v_add_f32_e32 v2, v2, v19
	s_waitcnt vmcnt(0)
	v_add_f32_e32 v2, v2, v20
	ds_write_b32 v6, v2

; __device__ __forceinline__ u32x2 pack4(const f32x4& v) { u32x2 w; w.x = pk2(v[0], v[1]); w.y = pk2(v[2], v[3]); return w; }
; __device__ __forceinline__ f32x4 unpack4(const u32x2& x) { return (f32x4){bf2f(x.x & 0xffffu), __uint_as_float(x.x & 0xffff0000u), bf2f(x.y & 0xffffu), __uint_as_float(x.y & 0xffff0000u)}; }
; __device__ __forceinline__ void nsa_prompt_unit(Frame& F, int l, int b, int kvh, int c) {
;     ...
;     bf16_t* ao = (bf16_t*)(F.ws + WS_ABR + SZ_ABR1) + (size_t)tok * 1024 + head * 64;
;     const bf16_t* az = P + (size_t)tok * NPROJ + C_AZ + head * 64;
; #pragma unroll
;     for (int i4 = 0; i4 < 8; ++i4) { const int d = 32 * (i4 >> 2) + 8 * (i4 & 3) + 4 * h;
;         const f32x4 t = ltot[i4 * 512]; const f32x4 zz = unpack4(*(const u32x2*)(az + d));
;         *(u32x2*)(ao + d) = pack4(t * zz); }
.LBB0_792:
	v_lshlrev_b64 v[2:3], 11, v[128:129]
	v_lshl_add_u64 v[2:3], s[52:53], 0, v[2:3]
	v_lshlrev_b32_e32 v98, 1, v171
	v_lshl_add_u64 v[2:3], v[2:3], 0, v[98:99]
	v_lshl_add_u64 v[4:5], v[130:131], 0, v[98:99]
	v_lshlrev_b32_e32 v98, 1, v138
	v_lshl_add_u64 v[4:5], v[4:5], 0, v[98:99]
	s_mov_b64 s[22:23], 0x2400
	v_lshl_add_u64 v[8:9], v[4:5], 0, s[22:23]
	v_lshl_add_u64 v[6:7], v[2:3], 0, v[98:99]
	global_load_dwordx2 v[42:43], v[8:9], off
	global_load_dwordx2 v[44:45], v[8:9], off offset:16
	global_load_dwordx2 v[46:47], v[8:9], off offset:32
	global_load_dwordx2 v[48:49], v[8:9], off offset:48
	global_load_dwordx2 v[50:51], v[8:9], off offset:64
	global_load_dwordx2 v[52:53], v[8:9], off offset:80
	global_load_dwordx2 v[54:55], v[8:9], off offset:96
	global_load_dwordx2 v[56:57], v[8:9], off offset:112
	ds_read_b128 v[58:61], v170 offset:32768
	ds_read_b128 v[62:65], v170 offset:40960
	ds_read_b128 v[66:69], v170 offset:49152
	ds_read_b128 v[70:73], v170 offset:57344
	s_and_b64 vcc, exec, s[58:59]
	s_waitcnt vmcnt(7)
	v_lshlrev_b32_e32 v10, 16, v42
	v_and_b32_e32 v11, 0xffff0000, v42
	v_lshlrev_b32_e32 v12, 16, v43
	v_and_b32_e32 v13, 0xffff0000, v43
	v_pk_mul_f32 v[10:11], v[38:39], v[10:11]
	v_pk_mul_f32 v[12:13], v[40:41], v[12:13]
	s_nop 0
	v_cvt_pk_bf16_f32 v10, v10, v11
	v_cvt_pk_bf16_f32 v11, v12, v13
	global_store_dwordx2 v[6:7], v[10:11], off
	s_waitcnt vmcnt(7)
	v_lshlrev_b32_e32 v14, 16, v44
	v_and_b32_e32 v15, 0xffff0000, v44
	v_lshlrev_b32_e32 v16, 16, v45
	v_and_b32_e32 v17, 0xffff0000, v45
	v_pk_mul_f32 v[14:15], v[34:35], v[14:15]
	v_pk_mul_f32 v[16:17], v[36:37], v[16:17]
	s_nop 0
	v_cvt_pk_bf16_f32 v14, v14, v15
	v_cvt_pk_bf16_f32 v15, v16, v17
	global_store_dwordx2 v[6:7], v[14:15], off offset:16
	s_waitcnt vmcnt(7)
	v_lshlrev_b32_e32 v10, 16, v46
	v_and_b32_e32 v11, 0xffff0000, v46
	v_lshlrev_b32_e32 v12, 16, v47
	v_and_b32_e32 v13, 0xffff0000, v47
	v_pk_mul_f32 v[10:11], v[22:23], v[10:11]
	v_pk_mul_f32 v[12:13], v[24:25], v[12:13]
	s_nop 0
	v_cvt_pk_bf16_f32 v10, v10, v11
	v_cvt_pk_bf16_f32 v11, v12, v13
	global_store_dwordx2 v[6:7], v[10:11], off offset:32
	s_waitcnt vmcnt(7)
	v_lshlrev_b32_e32 v14, 16, v48
	v_and_b32_e32 v15, 0xffff0000, v48
	v_lshlrev_b32_e32 v16, 16, v49
	v_and_b32_e32 v17, 0xffff0000, v49
	v_pk_mul_f32 v[14:15], v[18:19], v[14:15]
	v_pk_mul_f32 v[16:17], v[20:21], v[16:17]
	s_nop 0
	v_cvt_pk_bf16_f32 v14, v14, v15
	v_cvt_pk_bf16_f32 v15, v16, v17
	global_store_dwordx2 v[6:7], v[14:15], off offset:48
	s_waitcnt vmcnt(7) lgkmcnt(3)
	v_lshlrev_b32_e32 v10, 16, v50
	v_and_b32_e32 v11, 0xffff0000, v50
	v_lshlrev_b32_e32 v12, 16, v51
	v_and_b32_e32 v13, 0xffff0000, v51
	v_pk_mul_f32 v[10:11], v[58:59], v[10:11]
	v_pk_mul_f32 v[12:13], v[60:61], v[12:13]
	s_nop 0
	v_cvt_pk_bf16_f32 v10, v10, v11
	v_cvt_pk_bf16_f32 v11, v12, v13
	global_store_dwordx2 v[6:7], v[10:11], off offset:64
	s_waitcnt vmcnt(7) lgkmcnt(2)
	v_lshlrev_b32_e32 v14, 16, v52
	v_and_b32_e32 v15, 0xffff0000, v52
	v_lshlrev_b32_e32 v16, 16, v53
	v_and_b32_e32 v17, 0xffff0000, v53
	v_pk_mul_f32 v[14:15], v[62:63], v[14:15]
	v_pk_mul_f32 v[16:17], v[64:65], v[16:17]
	s_nop 0
	v_cvt_pk_bf16_f32 v14, v14, v15
	v_cvt_pk_bf16_f32 v15, v16, v17
	global_store_dwordx2 v[6:7], v[14:15], off offset:80
	s_waitcnt vmcnt(7) lgkmcnt(1)
	v_lshlrev_b32_e32 v10, 16, v54
	v_and_b32_e32 v11, 0xffff0000, v54
	v_lshlrev_b32_e32 v12, 16, v55
	v_and_b32_e32 v13, 0xffff0000, v55
	v_pk_mul_f32 v[10:11], v[66:67], v[10:11]
	v_pk_mul_f32 v[12:13], v[68:69], v[12:13]
	s_nop 0
	v_cvt_pk_bf16_f32 v10, v10, v11
	v_cvt_pk_bf16_f32 v11, v12, v13
	global_store_dwordx2 v[6:7], v[10:11], off offset:96
	s_waitcnt vmcnt(7) lgkmcnt(0)
	v_lshlrev_b32_e32 v14, 16, v56
	v_and_b32_e32 v15, 0xffff0000, v56
	v_lshlrev_b32_e32 v16, 16, v57
	v_and_b32_e32 v17, 0xffff0000, v57
	v_pk_mul_f32 v[14:15], v[70:71], v[14:15]
	v_pk_mul_f32 v[16:17], v[72:73], v[16:17]
	s_nop 0
	v_cvt_pk_bf16_f32 v14, v14, v15
	v_cvt_pk_bf16_f32 v15, v16, v17
	global_store_dwordx2 v[6:7], v[14:15], off offset:112
	s_cbranch_vccnz .LBB0_790

; __device__ __forceinline__ float flash_rowmax(const f32x16& s0, const f32x16& s1) {
;     float mx = -INFINITY;
; #pragma unroll
;     for (int i = 0; i < 16; ++i) asm("v_max3_f32 %0, %1, %2, %3" : "=v"(mx) : "v"(mx), "v"(s0[i]), "v"(s1[i]));
;     return xhalf_max(mx);
; }
; __device__ __forceinline__ void flash_pair(FlashState& S, const LAS unsigned char* ka, const LAS unsigned char* va, const LAS unsigned char* kb2, const LAS unsigned char* vb2, ...
;     ...
;     if (A.masked) flash_mask(a0, a1, A.lo, A.hi, h);
;     { const float mx = flash_rowmax(a0, a1);
;         if (__ballot(mx > SM_THR || (first && mx < -SM_THR)) != 0ull) { const float d = (mx > NEG_BIG) ? (first ? mx : fmaxf(mx, 0.f)) : 0.f, alpha = __builtin_amdgcn_exp2f(-d); S.m += d; S.l *= alpha;
; #pragma unroll
;             for (int i = 0; i < 16; ++i) { S.o[0][i] *= alpha; S.o[1][i] *= alpha; a0[i] -= d; a1[i] -= d; } } }
.LBB0_864:
	v_max3_f32 v34, v233, v82, v66
	s_mov_b32 s22, 0xc1000000
	v_max3_f32 v34, v34, v83, v67
	s_nop 0
	v_max3_f32 v34, v34, v84, v68
	s_nop 0
	v_max3_f32 v34, v34, v85, v69
	s_nop 0
	v_max3_f32 v34, v34, v86, v70
	s_nop 0
	v_max3_f32 v34, v34, v87, v71
	v_max3_f32 v34, v34, v88, v72
	v_max3_f32 v34, v34, v89, v73
	v_max3_f32 v34, v34, v90, v74
	v_max3_f32 v34, v34, v91, v75
	v_max3_f32 v34, v34, v92, v76
	v_max3_f32 v34, v34, v93, v77
	v_max3_f32 v34, v34, v94, v78
	v_max3_f32 v34, v34, v95, v79
	v_max3_f32 v34, v34, v96, v80
	v_max3_f32 v34, v34, v97, v81
	v_mov_b32_e32 v35, v34
	s_nop 1
	v_permlane32_swap_b32_e32 v34, v35
	v_max_f32_e32 v35, v35, v35
	v_max_f32_e32 v34, v34, v34
	v_max_f32_e32 v34, v34, v35
	v_cmp_gt_f32_e64 s[46:47], s22, v34
	v_cmp_lt_f32_e32 vcc, s33, v34
	s_and_b64 s[22:23], s[44:45], s[46:47]
	s_or_b64 s[22:23], vcc, s[22:23]
	v_cndmask_b32_e64 v35, 0, 1, s[22:23]
	v_cmp_ne_u32_e32 vcc, 0, v35
	s_cbranch_vccz .LBB0_866
	v_max_f32_e32 v35, v34, v34
	v_max_f32_e32 v35, 0, v35
	v_cndmask_b32_e64 v35, v35, v34, s[44:45]
	v_cmp_lt_f32_e32 vcc, s12, v34
	s_nop 1
	v_cndmask_b32_e32 v34, 0, v35, vcc
	v_exp_f32_e64 v36, -v34
	v_add_f32_e32 v173, v173, v34
	v_pk_add_f32 v[82:83], v[82:83], v[34:35] op_sel_hi:[1,0] neg_lo:[0,1] neg_hi:[0,1]
	v_pk_add_f32 v[66:67], v[66:67], v[34:35] op_sel_hi:[1,0] neg_lo:[0,1] neg_hi:[0,1]
	v_mul_f32_e32 v176, v176, v36
	v_pk_add_f32 v[84:85], v[84:85], v[34:35] op_sel_hi:[1,0] neg_lo:[0,1] neg_hi:[0,1]
	v_pk_add_f32 v[68:69], v[68:69], v[34:35] op_sel_hi:[1,0] neg_lo:[0,1] neg_hi:[0,1]
	v_pk_add_f32 v[86:87], v[86:87], v[34:35] op_sel_hi:[1,0] neg_lo:[0,1] neg_hi:[0,1]
	v_pk_add_f32 v[70:71], v[70:71], v[34:35] op_sel_hi:[1,0] neg_lo:[0,1] neg_hi:[0,1]
	v_pk_add_f32 v[88:89], v[88:89], v[34:35] op_sel_hi:[1,0] neg_lo:[0,1] neg_hi:[0,1]
	v_pk_add_f32 v[72:73], v[72:73], v[34:35] op_sel_hi:[1,0] neg_lo:[0,1] neg_hi:[0,1]
	v_pk_add_f32 v[90:91], v[90:91], v[34:35] op_sel_hi:[1,0] neg_lo:[0,1] neg_hi:[0,1]
	v_pk_add_f32 v[74:75], v[74:75], v[34:35] op_sel_hi:[1,0] neg_lo:[0,1] neg_hi:[0,1]
	v_pk_add_f32 v[92:93], v[92:93], v[34:35] op_sel_hi:[1,0] neg_lo:[0,1] neg_hi:[0,1]
	v_pk_add_f32 v[76:77], v[76:77], v[34:35] op_sel_hi:[1,0] neg_lo:[0,1] neg_hi:[0,1]
	v_pk_add_f32 v[94:95], v[94:95], v[34:35] op_sel_hi:[1,0] neg_lo:[0,1] neg_hi:[0,1]
	v_pk_add_f32 v[78:79], v[78:79], v[34:35] op_sel_hi:[1,0] neg_lo:[0,1] neg_hi:[0,1]
	v_pk_mul_f32 v[32:33], v[32:33], v[36:37] op_sel_hi:[1,0]
	v_pk_mul_f32 v[30:31], v[30:31], v[36:37] op_sel_hi:[1,0]
	v_pk_mul_f32 v[28:29], v[28:29], v[36:37] op_sel_hi:[1,0]
	v_pk_mul_f32 v[26:27], v[26:27], v[36:37] op_sel_hi:[1,0]
	v_pk_mul_f32 v[24:25], v[24:25], v[36:37] op_sel_hi:[1,0]
	v_pk_mul_f32 v[22:23], v[22:23], v[36:37] op_sel_hi:[1,0]
	v_pk_mul_f32 v[20:21], v[20:21], v[36:37] op_sel_hi:[1,0]
	v_pk_mul_f32 v[18:19], v[18:19], v[36:37] op_sel_hi:[1,0]
	v_pk_mul_f32 v[16:17], v[16:17], v[36:37] op_sel_hi:[1,0]
	v_pk_mul_f32 v[14:15], v[14:15], v[36:37] op_sel_hi:[1,0]
	v_pk_mul_f32 v[12:13], v[12:13], v[36:37] op_sel_hi:[1,0]
	v_pk_mul_f32 v[10:11], v[10:11], v[36:37] op_sel_hi:[1,0]
	v_pk_mul_f32 v[8:9], v[8:9], v[36:37] op_sel_hi:[1,0]
	v_pk_mul_f32 v[6:7], v[6:7], v[36:37] op_sel_hi:[1,0]
	v_pk_mul_f32 v[4:5], v[4:5], v[36:37] op_sel_hi:[1,0]
	v_pk_mul_f32 v[2:3], v[2:3], v[36:37] op_sel_hi:[1,0]
	v_pk_add_f32 v[96:97], v[96:97], v[34:35] op_sel_hi:[1,0] neg_lo:[0,1] neg_hi:[0,1]
	v_pk_add_f32 v[80:81], v[80:81], v[34:35] op_sel_hi:[1,0] neg_lo:[0,1] neg_hi:[0,1]

; __device__ __forceinline__ void flash_pair(FlashState& S, const LAS unsigned char* ka, const LAS unsigned char* va, const LAS unsigned char* kb2, const LAS unsigned char* vb2, ...
;     ...
;     bf16x8 pa[4]; float ls = 0.f;
; #pragma unroll
;     for (int i = 0; i < 16; ++i) ls += a0[i] + a1[i];
;     pa[0] = pack_p(a0, 0); pa[1] = pack_p(a0, 1); pa[2] = pack_p(a1, 0); pa[3] = pack_p(a1, 1);
;     S.l += ls;
;     __builtin_amdgcn_sched_barrier(0);
;     if (B.masked) flash_mask(b0, b1, B.lo, B.hi, h);
;     float alphaB = 1.f;
;     { const float mx = flash_rowmax(b0, b1);
;         if (__ballot(mx > SM_THR) != 0ull) { const float d = (mx > NEG_BIG) ? fmaxf(mx, 0.f) : 0.f; alphaB = __builtin_amdgcn_exp2f(-d); S.m += d; S.l *= alphaB;
; #pragma unroll
;             for (int i = 0; i < 16; ++i) { b0[i] -= d; b1[i] -= d; } } }
.LBB0_868:
	v_add_f32_e32 v78, v82, v66
	v_add_f32_e32 v78, 0, v78
	v_add_f32_e32 v79, v83, v67
	v_add_f32_e32 v78, v78, v79
	v_add_f32_e32 v79, v84, v68
	v_add_f32_e32 v78, v78, v79
	v_add_f32_e32 v79, v85, v69
	v_add_f32_e32 v78, v78, v79
	v_add_f32_e32 v79, v177, v70
	v_add_f32_e32 v78, v78, v79
	v_add_f32_e32 v79, v178, v71
	v_add_f32_e32 v78, v78, v79
	v_add_f32_e32 v79, v88, v72
	v_add_f32_e32 v78, v78, v79
	v_add_f32_e32 v79, v89, v73
	v_add_f32_e32 v78, v78, v79
	v_add_f32_e32 v79, v90, v74
	v_add_f32_e32 v78, v78, v79
	v_add_f32_e32 v79, v91, v75
	v_add_f32_e32 v78, v78, v79
	v_add_f32_e32 v79, v92, v76
	v_add_f32_e32 v78, v78, v79
	v_add_f32_e32 v79, v93, v77
	v_add_f32_e32 v78, v78, v79
	v_add_f32_e32 v79, v94, v116
	v_add_f32_e32 v78, v78, v79
	v_add_f32_e32 v79, v95, v117
	v_add_f32_e32 v78, v78, v79
	v_add_f32_e32 v79, v96, v118
	v_add_f32_e32 v78, v78, v79
	v_add_f32_e32 v79, v97, v119
	v_add_f32_e32 v78, v78, v79
	v_add_f32_e32 v87, v176, v78
	v_max3_f32 v78, v233, v50, v34
	v_max3_f32 v78, v78, v51, v35
	v_max3_f32 v78, v78, v52, v36
	v_max3_f32 v78, v78, v53, v37
	v_max3_f32 v78, v78, v54, v38
	v_max3_f32 v78, v78, v55, v39
	v_max3_f32 v78, v78, v56, v40
	v_max3_f32 v78, v78, v57, v41
	v_max3_f32 v78, v78, v58, v42
	v_max3_f32 v78, v78, v59, v43
	v_max3_f32 v78, v78, v60, v44
	v_max3_f32 v78, v78, v61, v45
	v_max3_f32 v78, v78, v62, v46
	v_max3_f32 v78, v78, v63, v47
	v_max3_f32 v78, v78, v64, v48
	v_max3_f32 v78, v78, v65, v49
	v_mov_b32_e32 v79, v78
	s_nop 1
	v_permlane32_swap_b32_e32 v78, v79
	v_max_f32_e32 v79, v79, v79
	v_max_f32_e32 v78, v78, v78
	v_max_f32_e32 v78, v78, v79
	v_cmp_lt_f32_e32 vcc, s33, v78
	s_cbranch_vccz .LBB0_870
	v_cmp_lt_f32_e32 vcc, s12, v78
	v_max_f32_e32 v78, v78, v78
	v_max_f32_e32 v78, 0, v78
	v_cndmask_b32_e32 v78, 0, v78, vcc
	v_exp_f32_e64 v86, -v78
	v_add_f32_e32 v173, v173, v78
	v_pk_add_f32 v[50:51], v[50:51], v[78:79] op_sel_hi:[1,0] neg_lo:[0,1] neg_hi:[0,1]
	v_pk_add_f32 v[34:35], v[34:35], v[78:79] op_sel_hi:[1,0] neg_lo:[0,1] neg_hi:[0,1]
	v_mul_f32_e32 v87, v87, v86
	v_pk_add_f32 v[52:53], v[52:53], v[78:79] op_sel_hi:[1,0] neg_lo:[0,1] neg_hi:[0,1]
	v_pk_add_f32 v[36:37], v[36:37], v[78:79] op_sel_hi:[1,0] neg_lo:[0,1] neg_hi:[0,1]
	v_pk_add_f32 v[54:55], v[54:55], v[78:79] op_sel_hi:[1,0] neg_lo:[0,1] neg_hi:[0,1]
	v_pk_add_f32 v[38:39], v[38:39], v[78:79] op_sel_hi:[1,0] neg_lo:[0,1] neg_hi:[0,1]
	v_pk_add_f32 v[56:57], v[56:57], v[78:79] op_sel_hi:[1,0] neg_lo:[0,1] neg_hi:[0,1]
	v_pk_add_f32 v[40:41], v[40:41], v[78:79] op_sel_hi:[1,0] neg_lo:[0,1] neg_hi:[0,1]
	v_pk_add_f32 v[58:59], v[58:59], v[78:79] op_sel_hi:[1,0] neg_lo:[0,1] neg_hi:[0,1]
	v_pk_add_f32 v[42:43], v[42:43], v[78:79] op_sel_hi:[1,0] neg_lo:[0,1] neg_hi:[0,1]
	v_pk_add_f32 v[60:61], v[60:61], v[78:79] op_sel_hi:[1,0] neg_lo:[0,1] neg_hi:[0,1]
	v_pk_add_f32 v[44:45], v[44:45], v[78:79] op_sel_hi:[1,0] neg_lo:[0,1] neg_hi:[0,1]
	v_pk_add_f32 v[62:63], v[62:63], v[78:79] op_sel_hi:[1,0] neg_lo:[0,1] neg_hi:[0,1]
	v_pk_add_f32 v[46:47], v[46:47], v[78:79] op_sel_hi:[1,0] neg_lo:[0,1] neg_hi:[0,1]
	v_pk_add_f32 v[64:65], v[64:65], v[78:79] op_sel_hi:[1,0] neg_lo:[0,1] neg_hi:[0,1]
	v_pk_add_f32 v[48:49], v[48:49], v[78:79] op_sel_hi:[1,0] neg_lo:[0,1] neg_hi:[0,1]
	s_branch .LBB0_871
